# attention sample units: K/V window staging unrolled, all global loads of the unit in flight at once (was 6 serial load-wait-convert-write round trips)
# speedup vs baseline: 1.0042x; 1.0042x over previous
.LBB0_569:
	s_add_i32 s10, s17, 0xfffff7e0
	s_and_b32 s18, s17, 7
	s_and_b32 s6, s10, -8
	s_barrier
	s_and_saveexec_b64 s[8:9], s[38:39]
	s_cbranch_execz .LBB0_586
	s_lshl_b32 s10, s10, 7
	s_and_b32 s19, s10, 0xfffffc00
	v_readlane_b32 s10, v253, 63
	v_readlane_b32 s11, v254, 0
	s_lshl_b32 s10, s18, 7
	s_mov_b32 s3, s11
	s_add_i32 s7, s6, 0x1fc0
	s_lshl_b32 s20, s18, 6
	s_or_b32 s21, s19, s18
	v_writelane_b32 v253, s2, 63
	v_lshl_add_u64 v[0:1], v[22:23], 0, s[10:11]
	v_writelane_b32 v254, s3, 0
	v_and_b32_e32 v128, -8, v76
	v_add_u32_e32 v128, s21, v128
	v_ashrrev_i32_e32 v129, 31, v128
	v_lshlrev_b64 v[128:129], 8, v[128:129]
	v_lshl_add_u64 v[128:129], v[26:27], 0, v[128:129]
	global_load_dwordx4 v[84:87], v[128:129], off
	global_load_dwordx4 v[88:91], v[128:129], off offset:16
	s_mov_b64 s[14:15], 0x20000
	v_lshl_add_u64 v[130:131], v[128:129], 0, s[14:15]
	global_load_dwordx4 v[92:95], v[130:131], off
	global_load_dwordx4 v[96:99], v[130:131], off offset:16
	v_and_b32_e32 v132, 0xffffffc0, v76
	v_add_u32_e32 v132, s19, v132
	v_or_b32_e32 v132, s18, v132
	v_ashrrev_i32_e32 v133, 31, v132
	v_lshlrev_b64 v[132:133], 8, v[132:133]
	v_lshl_add_u64 v[132:133], v[28:29], 0, v[132:133]
	s_mov_b64 s[12:13], 0x1000
	global_load_dword v108, v[132:133], off
	global_load_dword v109, v[132:133], off offset:2048
	v_lshl_add_u64 v[134:135], v[132:133], 0, s[12:13]
	global_load_dword v110, v[134:135], off
	global_load_dword v111, v[134:135], off offset:2048
	v_lshl_add_u64 v[134:135], v[134:135], 0, s[12:13]
	global_load_dword v112, v[134:135], off
	global_load_dword v113, v[134:135], off offset:2048
	v_lshl_add_u64 v[134:135], v[134:135], 0, s[12:13]
	global_load_dword v114, v[134:135], off
	global_load_dword v115, v[134:135], off offset:2048
	v_lshl_add_u64 v[132:133], v[132:133], 0, s[14:15]
	global_load_dword v116, v[132:133], off
	global_load_dword v117, v[132:133], off offset:2048
	v_lshl_add_u64 v[134:135], v[132:133], 0, s[12:13]
	global_load_dword v118, v[134:135], off
	global_load_dword v119, v[134:135], off offset:2048
	v_lshl_add_u64 v[134:135], v[134:135], 0, s[12:13]
	global_load_dword v120, v[134:135], off
	global_load_dword v121, v[134:135], off offset:2048
	v_lshl_add_u64 v[134:135], v[134:135], 0, s[12:13]
	global_load_dword v122, v[134:135], off
	global_load_dword v123, v[134:135], off offset:2048
	v_mov_b32_e32 v104, 0
	v_mov_b32_e32 v105, 0
	v_mov_b32_e32 v106, 0
	v_mov_b32_e32 v107, 0
	v_mov_b32_e32 v124, 0
	v_mov_b32_e32 v125, 0
	v_mov_b32_e32 v126, 0
	v_mov_b32_e32 v127, 0
	v_cmp_gt_u32_e32 vcc, 64, v76
	s_and_saveexec_b64 s[12:13], vcc
	v_lshrrev_b32_e32 v142, 3, v76
	v_add_u32_e32 v142, 0x80, v142
	v_add_u32_e32 v142, s7, v142
	v_ashrrev_i32_e32 v143, 31, v142
	v_lshlrev_b64 v[142:143], 10, v[142:143]
	v_lshl_add_u64 v[142:143], v[0:1], 0, v[142:143]
	global_load_dwordx4 v[104:107], v[142:143], off
	v_or_b32_e32 v144, s20, v35
	v_mul_u32_u24_e32 v144, 0x2200, v144
	v_readlane_b32 s10, v252, 31
	v_lshlrev_b32_e32 v144, 1, v144
	v_mov_b32_e32 v145, v2
	v_readlane_b32 s11, v252, 32
	s_ashr_i32 s7, s6, 31
	s_nop 1
	v_lshl_add_u64 v[144:145], s[10:11], 0, v[144:145]
	v_lshl_add_u64 v[144:145], s[6:7], 1, v[144:145]
	s_mov_b64 s[10:11], 0x4080
	v_lshl_add_u64 v[144:145], v[144:145], 0, s[10:11]
	global_load_dwordx4 v[124:127], v[144:145], off
	s_or_b64 exec, exec, s[12:13]
	v_lshrrev_b32_e32 v146, 3, v76
	s_movk_i32 s3, 0x90
	v_mad_u32_u24 v146, v146, s3, v24
	v_lshrrev_b32_e32 v147, 6, v76
	v_lshl_add_u32 v147, v147, 4, v36
	s_waitcnt vmcnt(0)
	v_cvt_pk_bf16_f32 v84, v84, v85
	v_cvt_pk_bf16_f32 v85, v86, v87
	v_cvt_pk_bf16_f32 v86, v88, v89
	v_cvt_pk_bf16_f32 v87, v90, v91
	v_cvt_pk_bf16_f32 v92, v92, v93
	v_cvt_pk_bf16_f32 v93, v94, v95
	v_cvt_pk_bf16_f32 v94, v96, v97
	v_cvt_pk_bf16_f32 v95, v98, v99
	ds_write_b128 v146, v[84:87]
	ds_write_b128 v146, v[92:95] offset:9216
	v_cvt_pk_bf16_f32 v108, v108, v109
	v_cvt_pk_bf16_f32 v109, v110, v111
	v_cvt_pk_bf16_f32 v110, v112, v113
	v_cvt_pk_bf16_f32 v111, v114, v115
	v_cvt_pk_bf16_f32 v116, v116, v117
	v_cvt_pk_bf16_f32 v117, v118, v119
	v_cvt_pk_bf16_f32 v118, v120, v121
	v_cvt_pk_bf16_f32 v119, v122, v123
	ds_write_b128 v147, v[108:111] offset:23040
	ds_write_b128 v147, v[116:119] offset:23168
	v_cmp_gt_u32_e32 vcc, 0x100, v76
	s_and_b64 exec, exec, vcc
	ds_write_b128 v146, v[104:107] offset:18432
	ds_write_b128 v147, v[124:127] offset:23296
